# mixprep item remap: 16 WGs run latent-C + ctx-C, their A/B stages and ctx A/B items spread over other WGs (balances the phase)
# speedup vs baseline: 1.0371x; 1.0123x over previous
.LBB0_260:
	s_add_i32 s29, s29, s42
	s_cmpk_gt_i32 s29, 0x14f
	s_cbranch_scc1 .LBB0_323
.LBB0_261:
	s_mov_b32 s8, s29
	s_mov_b32 s10, 7
	s_cmpk_lt_i32 s29, 0x100
	s_cbranch_scc0 .Lmp_second
	s_cmpk_lt_i32 s29, 16
	s_cbranch_scc0 .LBB0_265
	s_mov_b32 s10, 4
	s_branch .LBB0_265
.Lmp_second:
	s_and_b32 s6, s29, 0xff
	s_and_b32 s4, s6, 15
	s_lshr_b32 s5, s6, 4
	s_mov_b32 s8, s4
	s_or_b32 s6, s4, 0x100
	s_cmp_eq_u32 s5, 0
	s_cselect_b32 s8, s6, s8
	s_cmp_gt_u32 s5, 2
	s_cselect_b32 s8, s6, s8
	s_mov_b32 s10, 4
	s_cmp_eq_u32 s5, 0
	s_cbranch_scc1 .LBB0_265
	s_and_b32 s4, s5, 1
	s_cmp_eq_u32 s4, 1
	s_cselect_b32 s10, 1, 2
